# v30 + P4a rmsnorm lane reductions via DPP adds instead of ds_bpermute round trips (bit-identical)
# speedup vs baseline: 1.0086x; 1.0082x over previous
; __device__ __forceinline__ unsigned cvtpk(float lo, float hi) { f32x2 v = {lo, hi}; bf16x2_t b = __builtin_convertvector(v, bf16x2_t); return __builtin_bit_cast(unsigned, b); }
; __device__ __forceinline__ float bflo(unsigned u) { return __uint_as_float(u << 16); }
; __device__ __forceinline__ float bfhi(unsigned u) { return __uint_as_float(u & 0xffff0000u); }
; __global__ void __launch_bounds__(512, 2) fwd_kernel(Params p) {
;     ...
;         for (int r0 = 4 * gw; r0 < M; r0 += 4 * NGW) {
;             if (l == 1 && (r0 % TOK) < CTXL) continue;
;             const int r = r0 + (lane >> 4), l16 = lane & 15;
;             u32x4 ov[4], gv[4];
; #pragma unroll
;             for (int hh = 0; hh < 4; ++hh) { ov[hh] = *(const u32x4*)(OT + (size_t)r * 512 + hh * 128 + 8 * l16); gv[hh] = *(const u32x4*)(Z + (size_t)r * ZP + ZYG + hh * 128 + 8 * l16); }
;             const f32x4 gn0 = *(const f32x4*)(p.gla_norm + l * 128 + 8 * l16), gn1 = *(const f32x4*)(p.gla_norm + l * 128 + 8 * l16 + 4);
; #pragma unroll
;             for (int hh = 0; hh < 4; ++hh) {
;                 float o[8] = {bflo(ov[hh].x), bfhi(ov[hh].x), bflo(ov[hh].y), bfhi(ov[hh].y), bflo(ov[hh].z), bfhi(ov[hh].z), bflo(ov[hh].w), bfhi(ov[hh].w)};
;                 float s = 0.f;
; #pragma unroll
;                 for (int j = 0; j < 8; ++j) s += o[j] * o[j];
;                 s += __shfl_xor(s, 1); s += __shfl_xor(s, 2); s += __shfl_xor(s, 4); s += __shfl_xor(s, 8);
;                 const float rs = __builtin_amdgcn_rsqf(s * (1.f / 128.f) + EPS);
;                 const float gt[8] = {bflo(gv[hh].x), bfhi(gv[hh].x), bflo(gv[hh].y), bfhi(gv[hh].y), bflo(gv[hh].z), bfhi(gv[hh].z), bflo(gv[hh].w), bfhi(gv[hh].w)};
;                 u32x4 ow; ow.x = cvtpk(o[0] * rs * gn0[0] * gt[0], o[1] * rs * gn0[1] * gt[1]); ow.y = cvtpk(o[2] * rs * gn0[2] * gt[2], o[3] * rs * gn0[3] * gt[3]);
;                 ow.z = cvtpk(o[4] * rs * gn1[0] * gt[4], o[5] * rs * gn1[1] * gt[5]); ow.w = cvtpk(o[6] * rs * gn1[2] * gt[6], o[7] * rs * gn1[3] * gt[7]);
.LBB0_774:
	s_mul_hi_i32 s1, s0, 0x38e38e39
	s_lshr_b32 s2, s1, 31
	s_ashr_i32 s1, s1, 9
	s_add_i32 s1, s1, s2
	s_mulk_i32 s1, 0x900
	s_sub_i32 s1, s0, s1
	s_cmpk_lt_i32 s1, 0x100
	s_cselect_b64 s[2:3], -1, 0
	s_and_b64 s[2:3], s[62:63], s[2:3]
	s_and_b64 vcc, exec, s[2:3]
	s_cbranch_vccnz .LBB0_773
	v_add_u32_e32 v2, s0, v50
	v_ashrrev_i32_e32 v3, 31, v2
	v_lshlrev_b64 v[4:5], 10, v[2:3]
	v_lshl_add_u64 v[4:5], v[42:43], 0, v[4:5]
	global_load_dwordx4 v[34:37], v[4:5], off
	v_mov_b64_e32 v[6:7], s[88:89]
	v_mad_i64_i32 v[2:3], s[2:3], v2, s13, v[6:7]
	v_lshl_add_u64 v[2:3], v[2:3], 0, v[0:1]
	v_add_co_u32_e32 v48, vcc, 0x1000, v2
	s_mov_b64 s[2:3], 0x1800
	s_nop 0
	v_addc_co_u32_e32 v49, vcc, 0, v3, vcc
	v_lshl_add_u64 v[46:47], v[2:3], 0, s[2:3]
	global_load_dwordx4 v[38:41], v[48:49], off offset:2048
	global_load_dwordx4 v[30:33], v[4:5], off offset:256
	global_load_dwordx4 v[26:29], v[46:47], off offset:256
	global_load_dwordx4 v[22:25], v[4:5], off offset:512
	global_load_dwordx4 v[18:21], v[46:47], off offset:512
	global_load_dwordx4 v[14:17], v[4:5], off offset:768
	global_load_dwordx4 v[10:13], v[46:47], off offset:768
	s_nop 0
	global_load_dwordx4 v[2:5], v[44:45], off offset:16
	global_load_dwordx4 v[6:9], v[44:45], off
	v_and_b32_e32 v52, 64, v203
	v_xor_b32_e32 v51, 1, v203
	v_add_u32_e32 v54, 64, v52
	v_cmp_lt_i32_e32 vcc, v51, v54
	v_xor_b32_e32 v52, 2, v203
	v_xor_b32_e32 v55, 8, v203
	v_cndmask_b32_e32 v51, v203, v51, vcc
	v_lshlrev_b32_e32 v51, 2, v51
	v_cmp_lt_i32_e32 vcc, v52, v54
	s_waitcnt vmcnt(0)
	v_lshlrev_b32_e32 v70, 16, v34
	v_and_b32_e32 v71, 0xffff0000, v34
	v_lshlrev_b32_e32 v62, 16, v36
	v_lshlrev_b32_e32 v60, 16, v41
	v_and_b32_e32 v61, 0xffff0000, v41
	v_lshlrev_b32_e32 v64, 16, v40
	v_and_b32_e32 v65, 0xffff0000, v40
	v_lshlrev_b32_e32 v40, 16, v35
	v_and_b32_e32 v41, 0xffff0000, v35
	v_pk_mul_f32 v[34:35], v[70:71], v[70:71]
	v_pk_mul_f32 v[66:67], v[40:41], v[40:41]
	v_add_f32_e32 v34, v34, v35
	v_and_b32_e32 v63, 0xffff0000, v36
	v_add_f32_e32 v34, v34, v66
	v_lshlrev_b32_e32 v56, 16, v37
	v_and_b32_e32 v57, 0xffff0000, v37
	v_pk_mul_f32 v[36:37], v[62:63], v[62:63]
	v_add_f32_e32 v34, v34, v67
	v_add_f32_e32 v34, v34, v36
	v_pk_mul_f32 v[58:59], v[56:57], v[56:57]
	v_add_f32_e32 v34, v34, v37
	v_add_f32_e32 v34, v34, v58
	v_add_f32_e32 v34, v34, v59
	v_cndmask_b32_e32 v52, v203, v52, vcc
	v_lshlrev_b32_e32 v53, 2, v52
	v_xor_b32_e32 v52, 4, v203
	v_cmp_lt_i32_e32 vcc, v52, v54
	s_nop 1
	v_add_f32_dpp v34, v34, v34 quad_perm:[1,0,3,2] row_mask:0xf bank_mask:0xf
	v_cndmask_b32_e32 v52, v203, v52, vcc
	v_lshlrev_b32_e32 v52, 2, v52
	v_cmp_lt_i32_e32 vcc, v55, v54
	v_lshlrev_b32_e32 v72, 16, v38
	s_nop 1
	v_add_f32_dpp v34, v34, v34 quad_perm:[2,3,0,1] row_mask:0xf bank_mask:0xf
	v_cndmask_b32_e32 v54, v203, v55, vcc
	v_lshlrev_b32_e32 v54, 2, v54
	v_and_b32_e32 v73, 0xffff0000, v38
	v_lshlrev_b32_e32 v68, 16, v39
	s_nop 1
	v_add_f32_dpp v34, v34, v34 row_half_mirror row_mask:0xf bank_mask:0xf
	v_and_b32_e32 v69, 0xffff0000, v39
	s_nop 1
	v_add_f32_dpp v34, v34, v34 row_mirror row_mask:0xf bank_mask:0xf
	v_fmamk_f32 v34, v34, 0x3c000000, v202
	v_rsq_f32_e32 v38, v34
	s_nop 0
	v_pk_mul_f32 v[34:35], v[38:39], v[70:71] op_sel_hi:[0,1]
	v_pk_mul_f32 v[36:37], v[38:39], v[40:41] op_sel_hi:[0,1]
	v_pk_mul_f32 v[34:35], v[6:7], v[34:35]
	v_pk_mul_f32 v[36:37], v[8:9], v[36:37]
	v_pk_mul_f32 v[34:35], v[34:35], v[72:73]
	v_pk_mul_f32 v[36:37], v[36:37], v[68:69]
	v_cvt_pk_bf16_f32 v34, v34, v35
	v_cvt_pk_bf16_f32 v35, v36, v37
	v_pk_mul_f32 v[36:37], v[38:39], v[62:63] op_sel_hi:[0,1]
	v_pk_mul_f32 v[38:39], v[38:39], v[56:57] op_sel_hi:[0,1]
	v_pk_mul_f32 v[36:37], v[2:3], v[36:37]
	v_pk_mul_f32 v[38:39], v[4:5], v[38:39]
	v_pk_mul_f32 v[36:37], v[36:37], v[64:65]
	v_pk_mul_f32 v[38:39], v[38:39], v[60:61]
	v_cvt_pk_bf16_f32 v36, v36, v37
	v_cvt_pk_bf16_f32 v37, v38, v39
	v_lshlrev_b32_e32 v60, 16, v30
	v_and_b32_e32 v61, 0xffff0000, v30
	global_store_dwordx4 v[48:49], v[34:37], off offset:2048
	v_lshlrev_b32_e32 v38, 16, v32
	v_and_b32_e32 v39, 0xffff0000, v32
	v_lshlrev_b32_e32 v34, 16, v33
	v_and_b32_e32 v35, 0xffff0000, v33
	v_lshlrev_b32_e32 v36, 16, v29
	v_and_b32_e32 v37, 0xffff0000, v29
	v_lshlrev_b32_e32 v32, 16, v28
	v_and_b32_e32 v33, 0xffff0000, v28
	v_lshlrev_b32_e32 v28, 16, v31
	v_and_b32_e32 v29, 0xffff0000, v31
	v_pk_mul_f32 v[30:31], v[60:61], v[60:61]
	v_pk_mul_f32 v[58:59], v[28:29], v[28:29]
	v_lshlrev_b32_e32 v62, 16, v26
	v_and_b32_e32 v63, 0xffff0000, v26
	v_add_f32_e32 v26, v30, v31
	v_add_f32_e32 v26, v26, v58
	v_pk_mul_f32 v[56:57], v[38:39], v[38:39]
	v_add_f32_e32 v26, v26, v59
	v_add_f32_e32 v26, v26, v56
	v_pk_mul_f32 v[48:49], v[34:35], v[34:35]
	v_add_f32_e32 v26, v26, v57
	v_add_f32_e32 v26, v26, v48
	v_add_f32_e32 v26, v26, v49
	v_lshlrev_b32_e32 v40, 16, v27
	v_and_b32_e32 v41, 0xffff0000, v27
	v_lshlrev_b32_e32 v48, 16, v18
	v_and_b32_e32 v49, 0xffff0000, v18
	s_nop 1
	v_add_f32_dpp v26, v26, v26 quad_perm:[1,0,3,2] row_mask:0xf bank_mask:0xf
	s_nop 1
	v_add_f32_dpp v26, v26, v26 quad_perm:[2,3,0,1] row_mask:0xf bank_mask:0xf
; __device__ __forceinline__ unsigned cvtpk(float lo, float hi) { f32x2 v = {lo, hi}; bf16x2_t b = __builtin_convertvector(v, bf16x2_t); return __builtin_bit_cast(unsigned, b); }
; __device__ __forceinline__ float bflo(unsigned u) { return __uint_as_float(u << 16); }
; __device__ __forceinline__ float bfhi(unsigned u) { return __uint_as_float(u & 0xffff0000u); }
; __global__ void __launch_bounds__(512, 2) fwd_kernel(Params p) {
;     ...
;             for (int hh = 0; hh < 4; ++hh) {
;                 float o[8] = {bflo(ov[hh].x), bfhi(ov[hh].x), bflo(ov[hh].y), bfhi(ov[hh].y), bflo(ov[hh].z), bfhi(ov[hh].z), bflo(ov[hh].w), bfhi(ov[hh].w)};
;                 float s = 0.f;
; #pragma unroll
;                 for (int j = 0; j < 8; ++j) s += o[j] * o[j];
;                 s += __shfl_xor(s, 1); s += __shfl_xor(s, 2); s += __shfl_xor(s, 4); s += __shfl_xor(s, 8);
;                 const float rs = __builtin_amdgcn_rsqf(s * (1.f / 128.f) + EPS);
;                 const float gt[8] = {bflo(gv[hh].x), bfhi(gv[hh].x), bflo(gv[hh].y), bfhi(gv[hh].y), bflo(gv[hh].z), bfhi(gv[hh].z), bflo(gv[hh].w), bfhi(gv[hh].w)};
;                 u32x4 ow; ow.x = cvtpk(o[0] * rs * gn0[0] * gt[0], o[1] * rs * gn0[1] * gt[1]); ow.y = cvtpk(o[2] * rs * gn0[2] * gt[2], o[3] * rs * gn0[3] * gt[3]);
;                 ow.z = cvtpk(o[4] * rs * gn1[0] * gt[4], o[5] * rs * gn1[1] * gt[5]); ow.w = cvtpk(o[6] * rs * gn1[2] * gt[6], o[7] * rs * gn1[3] * gt[7]);
;                 if (!(rep == 0 && dryflag)) *(u32x4*)(Z + (size_t)r * ZP + ZYG + hh * 128 + 8 * l16) = ow;
	s_nop 1
	v_add_f32_dpp v26, v26, v26 row_half_mirror row_mask:0xf bank_mask:0xf
	s_nop 1
	v_add_f32_dpp v26, v26, v26 row_mirror row_mask:0xf bank_mask:0xf
	v_fmamk_f32 v26, v26, 0x3c000000, v202
	v_rsq_f32_e32 v30, v26
	s_nop 0
	v_pk_mul_f32 v[26:27], v[30:31], v[60:61] op_sel_hi:[0,1]
	v_pk_mul_f32 v[28:29], v[30:31], v[28:29] op_sel_hi:[0,1]
	v_pk_mul_f32 v[26:27], v[6:7], v[26:27]
	v_pk_mul_f32 v[28:29], v[8:9], v[28:29]
	v_pk_mul_f32 v[26:27], v[26:27], v[62:63]
	v_pk_mul_f32 v[28:29], v[28:29], v[40:41]
	v_cvt_pk_bf16_f32 v26, v26, v27
	v_cvt_pk_bf16_f32 v27, v28, v29
	v_pk_mul_f32 v[28:29], v[30:31], v[38:39] op_sel_hi:[0,1]
	v_pk_mul_f32 v[30:31], v[30:31], v[34:35] op_sel_hi:[0,1]
	v_pk_mul_f32 v[28:29], v[2:3], v[28:29]
	v_pk_mul_f32 v[30:31], v[4:5], v[30:31]
	v_pk_mul_f32 v[28:29], v[28:29], v[32:33]
	v_pk_mul_f32 v[30:31], v[30:31], v[36:37]
	v_lshlrev_b32_e32 v40, 16, v22
	v_and_b32_e32 v41, 0xffff0000, v22
	v_cvt_pk_bf16_f32 v28, v28, v29
	v_cvt_pk_bf16_f32 v29, v30, v31
	v_lshlrev_b32_e32 v30, 16, v21
	v_and_b32_e32 v31, 0xffff0000, v21
	v_lshlrev_b32_e32 v34, 16, v20
	v_and_b32_e32 v35, 0xffff0000, v20
	v_lshlrev_b32_e32 v20, 16, v23
	v_and_b32_e32 v21, 0xffff0000, v23
	v_pk_mul_f32 v[22:23], v[40:41], v[40:41]
	v_pk_mul_f32 v[36:37], v[20:21], v[20:21]
	v_add_f32_e32 v18, v22, v23
	v_lshlrev_b32_e32 v32, 16, v24
	v_and_b32_e32 v33, 0xffff0000, v24
	v_add_f32_e32 v18, v18, v36
	global_store_dwordx4 v[46:47], v[26:29], off offset:256
	v_add_f32_e32 v18, v18, v37
	v_lshlrev_b32_e32 v38, 16, v19
	v_lshlrev_b32_e32 v26, 16, v25
	v_and_b32_e32 v27, 0xffff0000, v25
	v_pk_mul_f32 v[24:25], v[32:33], v[32:33]
	v_pk_mul_f32 v[28:29], v[26:27], v[26:27]
	v_add_f32_e32 v18, v18, v24
	v_add_f32_e32 v18, v18, v25
	v_add_f32_e32 v18, v18, v28
	v_add_f32_e32 v18, v18, v29
	v_and_b32_e32 v39, 0xffff0000, v19
	v_lshlrev_b32_e32 v24, 16, v16
	v_and_b32_e32 v25, 0xffff0000, v16
	s_nop 1
	v_add_f32_dpp v18, v18, v18 quad_perm:[1,0,3,2] row_mask:0xf bank_mask:0xf
	s_nop 1
	v_add_f32_dpp v18, v18, v18 quad_perm:[2,3,0,1] row_mask:0xf bank_mask:0xf
	s_nop 1
	v_add_f32_dpp v18, v18, v18 row_half_mirror row_mask:0xf bank_mask:0xf
	s_nop 1
	v_add_f32_dpp v18, v18, v18 row_mirror row_mask:0xf bank_mask:0xf
	v_fmamk_f32 v18, v18, 0x3c000000, v202
	v_rsq_f32_e32 v22, v18
	s_nop 0
	v_pk_mul_f32 v[18:19], v[22:23], v[40:41] op_sel_hi:[0,1]
	v_pk_mul_f32 v[20:21], v[22:23], v[20:21] op_sel_hi:[0,1]
	v_pk_mul_f32 v[18:19], v[6:7], v[18:19]
	v_pk_mul_f32 v[20:21], v[8:9], v[20:21]
	v_pk_mul_f32 v[18:19], v[18:19], v[48:49]
	v_pk_mul_f32 v[20:21], v[20:21], v[38:39]
	v_cvt_pk_bf16_f32 v18, v18, v19
	v_cvt_pk_bf16_f32 v19, v20, v21
	v_pk_mul_f32 v[20:21], v[22:23], v[32:33] op_sel_hi:[0,1]
	v_pk_mul_f32 v[22:23], v[22:23], v[26:27] op_sel_hi:[0,1]
	v_pk_mul_f32 v[20:21], v[2:3], v[20:21]
	v_pk_mul_f32 v[22:23], v[4:5], v[22:23]
	v_pk_mul_f32 v[20:21], v[20:21], v[34:35]
	v_pk_mul_f32 v[22:23], v[22:23], v[30:31]
	v_lshlrev_b32_e32 v32, 16, v14
	v_and_b32_e32 v33, 0xffff0000, v14
	v_cvt_pk_bf16_f32 v20, v20, v21
	v_cvt_pk_bf16_f32 v21, v22, v23
	v_lshlrev_b32_e32 v22, 16, v13
	v_and_b32_e32 v23, 0xffff0000, v13
	v_lshlrev_b32_e32 v26, 16, v12
	v_and_b32_e32 v27, 0xffff0000, v12
	v_lshlrev_b32_e32 v12, 16, v15
	v_and_b32_e32 v13, 0xffff0000, v15
	v_pk_mul_f32 v[14:15], v[32:33], v[32:33]
	v_pk_mul_f32 v[28:29], v[12:13], v[12:13]
	v_lshlrev_b32_e32 v34, 16, v10
	v_and_b32_e32 v35, 0xffff0000, v10
	v_add_f32_e32 v10, v14, v15
	v_add_f32_e32 v10, v10, v28
	global_store_dwordx4 v[46:47], v[18:21], off offset:512
	v_add_f32_e32 v10, v10, v29
	v_lshlrev_b32_e32 v30, 16, v11
	v_lshlrev_b32_e32 v18, 16, v17
	v_and_b32_e32 v19, 0xffff0000, v17
	v_pk_mul_f32 v[16:17], v[24:25], v[24:25]
	v_pk_mul_f32 v[20:21], v[18:19], v[18:19]
	v_add_f32_e32 v10, v10, v16
	v_add_f32_e32 v10, v10, v17
	v_add_f32_e32 v10, v10, v20
	v_add_f32_e32 v10, v10, v21
	v_and_b32_e32 v31, 0xffff0000, v11
	s_nop 1
	v_add_f32_dpp v10, v10, v10 quad_perm:[1,0,3,2] row_mask:0xf bank_mask:0xf
	s_nop 1
	v_add_f32_dpp v10, v10, v10 quad_perm:[2,3,0,1] row_mask:0xf bank_mask:0xf
	s_nop 1
	v_add_f32_dpp v10, v10, v10 row_half_mirror row_mask:0xf bank_mask:0xf
	s_nop 1
	v_add_f32_dpp v10, v10, v10 row_mirror row_mask:0xf bank_mask:0xf
	v_fmamk_f32 v10, v10, 0x3c000000, v202
	v_rsq_f32_e32 v10, v10
	s_nop 0
	v_pk_mul_f32 v[14:15], v[10:11], v[32:33] op_sel_hi:[0,1]
	v_pk_mul_f32 v[12:13], v[10:11], v[12:13] op_sel_hi:[0,1]
	v_pk_mul_f32 v[6:7], v[6:7], v[14:15]
	v_pk_mul_f32 v[8:9], v[8:9], v[12:13]
	v_pk_mul_f32 v[6:7], v[6:7], v[34:35]
	v_pk_mul_f32 v[8:9], v[8:9], v[30:31]
	v_cvt_pk_bf16_f32 v6, v6, v7
	v_cvt_pk_bf16_f32 v7, v8, v9
	v_pk_mul_f32 v[8:9], v[10:11], v[24:25] op_sel_hi:[0,1]
	v_pk_mul_f32 v[2:3], v[2:3], v[8:9]
	s_nop 0
	v_pk_mul_f32 v[2:3], v[2:3], v[26:27]
	s_nop 0
	v_cvt_pk_bf16_f32 v8, v2, v3
	v_pk_mul_f32 v[2:3], v[10:11], v[18:19] op_sel_hi:[0,1]
	v_pk_mul_f32 v[2:3], v[4:5], v[2:3]
	s_nop 0
	v_pk_mul_f32 v[2:3], v[2:3], v[22:23]
	s_nop 0
	v_cvt_pk_bf16_f32 v9, v2, v3
	global_store_dwordx4 v[46:47], v[6:9], off offset:768
	s_branch .LBB0_773
